# final RMSNorm phase: nt hint on the once-read bf16 residual loads
# speedup vs baseline: 1.0160x; 1.0053x over previous
.LBB0_15:
	global_load_dwordx4 v[24:27], v[16:17], off
	global_load_dwordx4 v[28:31], v[16:17], off offset:16
	global_load_dwordx4 v[32:35], v[16:17], off offset:32
	global_load_dwordx4 v[36:39], v[16:17], off offset:48
	global_load_dwordx2 v[40:41], v[22:23], off offset:-1024 nt
	global_load_dwordx2 v[42:43], v[22:23], off offset:-512 nt
	global_load_dwordx2 v[44:45], v[22:23], off nt
	global_load_dwordx2 v[46:47], v[22:23], off offset:512 nt
	v_add_u32_e32 v21, s6, v21
	v_cmp_lt_i32_e32 vcc, s69, v21
	s_or_b64 s[14:15], vcc, s[14:15]
	v_lshl_add_u64 v[16:17], v[16:17], 0, s[8:9]
	v_lshl_add_u64 v[22:23], v[22:23], 0, s[12:13]
	s_waitcnt vmcnt(6)
	v_pk_add_f32 v[26:27], v[26:27], v[30:31]
	v_pk_add_f32 v[24:25], v[24:25], v[28:29]
	s_waitcnt vmcnt(4)
	v_pk_add_f32 v[28:29], v[34:35], v[38:39]
	v_pk_add_f32 v[30:31], v[32:33], v[36:37]
	v_pk_add_f32 v[26:27], v[26:27], v[28:29]
	v_pk_add_f32 v[24:25], v[24:25], v[30:31]
	s_waitcnt vmcnt(3)
	v_lshlrev_b32_e32 v32, 16, v40
	v_pk_mov_b32 v[28:29], v[24:25], v[26:27] op_sel:[1,0]
	v_mov_b32_e32 v25, v27
	v_pk_add_f32 v[24:25], v[28:29], v[24:25]
	v_and_b32_e32 v33, 0xffff0000, v40
	v_add_f32_e32 v24, v24, v25
	v_fmamk_f32 v24, v24, 0x3a800000, v191
	v_mul_f32_e32 v25, 0x4b800000, v24
	v_cmp_gt_f32_e32 vcc, s77, v24
	v_lshlrev_b32_e32 v34, 16, v41
	v_and_b32_e32 v35, 0xffff0000, v41
	v_cndmask_b32_e32 v24, v24, v25, vcc
	v_rsq_f32_e32 v24, v24
	s_waitcnt vmcnt(2)
	v_lshlrev_b32_e32 v36, 16, v42
	v_and_b32_e32 v37, 0xffff0000, v42
	v_lshlrev_b32_e32 v38, 16, v43
	v_mul_f32_e32 v25, 0x45800000, v24
	v_cndmask_b32_e32 v24, v24, v25, vcc
	v_and_b32_e32 v39, 0xffff0000, v43
	s_waitcnt vmcnt(1)
	v_lshlrev_b32_e32 v40, 16, v44
	v_and_b32_e32 v41, 0xffff0000, v44
	v_lshlrev_b32_e32 v42, 16, v45
	v_and_b32_e32 v43, 0xffff0000, v45
	s_waitcnt vmcnt(0)
	v_lshlrev_b32_e32 v44, 16, v46
	v_and_b32_e32 v45, 0xffff0000, v46
	v_lshlrev_b32_e32 v46, 16, v47
	v_and_b32_e32 v47, 0xffff0000, v47
	v_pk_mul_f32 v[28:29], v[24:25], v[32:33] op_sel_hi:[0,1]
	v_pk_mul_f32 v[26:27], v[24:25], v[34:35] op_sel_hi:[0,1]
	v_pk_mul_f32 v[32:33], v[24:25], v[36:37] op_sel_hi:[0,1]
	v_pk_mul_f32 v[30:31], v[24:25], v[38:39] op_sel_hi:[0,1]
	v_pk_mul_f32 v[36:37], v[24:25], v[40:41] op_sel_hi:[0,1]
	v_pk_mul_f32 v[34:35], v[24:25], v[42:43] op_sel_hi:[0,1]
	v_pk_mul_f32 v[40:41], v[24:25], v[44:45] op_sel_hi:[0,1]
	v_pk_mul_f32 v[38:39], v[24:25], v[46:47] op_sel_hi:[0,1]
	v_pk_mul_f32 v[26:27], v[2:3], v[26:27]
	v_pk_mul_f32 v[24:25], v[0:1], v[28:29]
	v_pk_mul_f32 v[30:31], v[6:7], v[30:31]
	v_pk_mul_f32 v[28:29], v[4:5], v[32:33]
	v_pk_mul_f32 v[34:35], v[10:11], v[34:35]
	v_pk_mul_f32 v[32:33], v[8:9], v[36:37]
	v_pk_mul_f32 v[38:39], v[14:15], v[38:39]
	v_pk_mul_f32 v[36:37], v[12:13], v[40:41]
	global_store_dwordx4 v[18:19], v[24:27], off offset:-2048
	global_store_dwordx4 v[18:19], v[28:31], off offset:-1024
	global_store_dwordx4 v[18:19], v[32:35], off
	global_store_dwordx4 v[18:19], v[36:39], off offset:1024
	v_lshl_add_u64 v[18:19], v[18:19], 0, s[10:11]
	s_andn2_b64 exec, exec, s[14:15]
	s_cbranch_execnz .LBB0_15
